# split barrier: completion words polled one step early (overlapped with the arrival atomic / the pass-A drain), waits only re-poll if not yet complete
# baseline (speedup 1.0000x reference)
.LBB0_263:
	s_mul_i32 s0, s96, 5
	s_add_i32 s4, s0, 3
	s_waitcnt vmcnt(0)
	s_barrier
	s_and_saveexec_b64 s[100:101], s[56:57]
	s_cbranch_execz .Lsb_aB_x
	v_readlane_b32 s98, v242, 47
	s_nop 3
	s_cmp_eq_u32 s98, 0
	s_cselect_b32 s99, 0, 128
	s_getreg_b32 s98, hwreg(HW_REG_XCC_ID, 0, 4)
	s_lshl_b32 s98, s98, 2
	s_add_u32 s98, s98, s99
	s_add_u32 s98, s98, 0x16370e40
	s_add_u32 s98, s68, s98
	s_addc_u32 s99, s69, 0
	v_mov_b32_e32 v246, 0
	v_mov_b32_e32 v247, 1
	global_atomic_add v247, v246, v247, s[98:99] sc0
	v_readlane_b32 s98, v242, 47
	s_nop 3
	s_cmp_eq_u32 s98, 0
	s_cselect_b32 s98, 0, 8
	s_add_u32 s98, s98, 0x16370d00
	s_add_u32 s98, s68, s98
	s_addc_u32 s99, s69, 0
	v_mov_b32_e32 v245, 0
	global_load_dword v245, v245, s[98:99] sc1
	v_mov_b32_e32 v246, 0x20ff0
	ds_read_b32 v246, v246
	s_waitcnt vmcnt(0) lgkmcnt(0)
	v_add_u32_e32 v247, 1, v247
	v_cmp_eq_u32_e32 vcc, v247, v246
	s_cbranch_vccz .Lsb_aB_x
	buffer_wbl2 sc1
	s_waitcnt vmcnt(0)
	v_readlane_b32 s98, v242, 47
	s_nop 3
	s_cmp_eq_u32 s98, 0
	s_cselect_b32 s98, 0, 8
	s_add_u32 s98, s98, 0x16370d04
	s_add_u32 s98, s68, s98
	s_addc_u32 s99, s69, 0
	v_mov_b32_e32 v246, 0
	v_mov_b32_e32 v247, 1
	global_atomic_add v246, v247, s[98:99]
	s_waitcnt vmcnt(0)
.Lsb_aB_x:
	s_or_b64 exec, exec, s[100:101]
	s_and_saveexec_b64 s[100:101], s[56:57]
	s_cbranch_execz .Lsb_wA_x
	v_readlane_b32 s98, v242, 47
	s_nop 3
	s_cmp_eq_u32 s98, 0
	s_cselect_b32 s98, 0, 8
	s_add_u32 s98, s98, 0x16370d00
	s_add_u32 s98, s68, s98
	s_addc_u32 s99, s69, 0
	v_mov_b32_e32 v247, 0x20ff4
	ds_read_b32 v247, v247
	s_waitcnt lgkmcnt(0)
	v_cmp_lt_u32_e32 vcc, v245, v247
	s_cbranch_vccz .Lsb_wA_g
	v_mov_b32_e32 v245, 0

.LBB0_361:
	s_and_saveexec_b64 s[100:101], s[56:57]
	s_cbranch_execz .Lsb_pB_x
	v_readlane_b32 s98, v242, 47
	s_nop 3
	s_cmp_eq_u32 s98, 0
	s_cselect_b32 s98, 0, 8
	s_add_u32 s98, s98, 0x16370d04
	s_add_u32 s98, s68, s98
	s_addc_u32 s99, s69, 0
	v_mov_b32_e32 v245, 0
	global_load_dword v245, v245, s[98:99] sc1
.Lsb_pB_x:
	s_or_b64 exec, exec, s[100:101]
	s_waitcnt vmcnt(0)
	s_barrier
	s_and_saveexec_b64 s[100:101], s[56:57]
	s_and_b32 s98, s2, 15
	s_lshl_b32 s99, s96, 4
	s_add_i32 s98, s98, s99
	s_lshl_b32 s98, s98, 2
	s_add_u32 s98, s98, 0x16370d80
	s_add_u32 s98, s68, s98
	s_addc_u32 s99, s69, 0
	v_mov_b32_e32 v246, 0
	v_mov_b32_e32 v247, 1
	global_atomic_add v246, v247, s[98:99]
	s_or_b64 exec, exec, s[100:101]
	s_and_saveexec_b64 s[100:101], s[56:57]
	s_cbranch_execz .Lsb_wB_x
	v_readlane_b32 s98, v242, 47
	s_nop 3
	s_cmp_eq_u32 s98, 0
	s_cselect_b32 s98, 0, 8
	s_add_u32 s98, s98, 0x16370d04
	s_add_u32 s98, s68, s98
	s_addc_u32 s99, s69, 0
	v_mov_b32_e32 v247, 0x20ff4
	ds_read_b32 v247, v247
	s_waitcnt lgkmcnt(0)
	v_cmp_lt_u32_e32 vcc, v245, v247
	s_cbranch_vccz .Lsb_wB_g
	v_mov_b32_e32 v245, 0
